# conversion slices spread over the arrive/wait gaps of steps 4, 6, 11 and 12 (barriers 3->4 and 11->12 also arrive-only)
# speedup vs baseline: 1.0250x; 1.0021x over previous
.LBB0_21:
	v_readlane_b32 s6, v244, 1
	v_readlane_b32 s7, v244, 2
	s_cmp_lt_u32 s70, 11
	v_readlane_b32 s0, v244, 3
	s_mov_b32 s71, s6
	s_cselect_b64 s[6:7], -1, 0
	s_add_i32 s20, s70, -9
	v_readlane_b32 s1, v244, 4
	v_readlane_b32 s3, v244, 0
	s_cmp_gt_u32 s70, 10
	s_cselect_b64 s[22:23], -1, 0
	s_waitcnt lgkmcnt(0)
	s_load_dwordx2 s[24:25], s[0:1], 0xb8
	s_and_b64 s[18:19], s[22:23], exec
	s_cselect_b32 s18, s20, s70
	s_cmp_lt_u32 s70, 2
	s_cselect_b32 s19, s70, s18
	s_cmpk_eq_u32 s71, 0x200
	s_cbranch_scc0 .Lhk_no
	s_cmp_eq_u32 s70, 4
	s_cbranch_scc1 .Lhk_g4
	s_cmp_eq_u32 s70, 6
	s_cbranch_scc1 .Lhk_g6
	s_cmp_eq_u32 s70, 11
	s_cbranch_scc1 .Lhk_g11
	s_cmp_eq_u32 s70, 12
	s_cbranch_scc1 .Lhk_g12
	s_branch .Lhk_no
.Lhk_g4:
	s_waitcnt lgkmcnt(0)
	s_branch .Lcv_g4

.LBB0_451:
	ds_read_b32 v0, v157 offset:4
	v_readlane_b32 s25, v244, 1
	s_mov_b32 s26, 0x4ae78
	s_lshr_b32 s26, s26, s70
	s_and_b32 s26, s26, 1
	s_cmpk_eq_u32 s25, 0x200
	s_cselect_b32 s25, s26, 0
	v_readlane_b32 s18, v244, 44
	v_readlane_b32 s19, v244, 45
	s_waitcnt lgkmcnt(0)
	v_readfirstlane_b32 s20, v3
	v_readfirstlane_b32 s21, v2
	v_add_u32_e32 v0, 1, v0
	s_nop 1
	v_readfirstlane_b32 s22, v0
	ds_write_b32 v157, v0 offset:4
	global_atomic_add v4, v1, v158, s[18:19] sc0
	buffer_inv sc1
	s_mul_i32 s23, s22, s20
	s_waitcnt vmcnt(1)
	v_readfirstlane_b32 s3, v4
	s_add_i32 s3, s3, 1
	s_cmp_eq_u32 s3, s23
	s_cbranch_scc1 .Lxb_lead
	s_cmp_lg_u32 s25, 0
	s_cbranch_scc0 .Lxb_full
	global_atomic_add v1, v158, s[18:19] offset:128
	s_branch .LBB0_19

.Lcv_s6a:
	s_mov_b32 s28, 0
	s_mov_b32 s29, 3
	s_add_i32 s26, s3, 0x260
	s_movk_i32 s27, 0x200
	s_movk_i32 s89, 0x1a00
	s_branch .Lcv_go

.Lcv_s11:
	s_mov_b32 s28, 1
	s_mov_b32 s29, 3
	s_add_i32 s26, s3, 0x1e0
	s_movk_i32 s27, 0x200
	s_movk_i32 s89, 0x10cc
	s_branch .Lcv_go
.Lcv_g12:
	s_mov_b32 s28, 1
	s_mov_b32 s29, 3
	s_add_i32 s26, s3, 0x433
	s_movk_i32 s27, 0x200
	s_movk_i32 s89, 0x1a00
	s_branch .Lcv_go

.Lcv_done:
	s_cmp_eq_u32 s29, 0
	s_cbranch_scc1 .Lcv_p0b
	s_cmp_eq_u32 s29, 1
	s_cbranch_scc1 .LBB0_518
	s_cmp_eq_u32 s29, 3
	s_cbranch_scc0 .LBB0_435
	s_waitcnt vmcnt(0) lgkmcnt(0)
	s_barrier
	s_branch .Lcvret_disp
	s_branch .LBB0_435
